# strategy 9 (back-edge rotation, asm guide 7.11): in the FFN gate/up K-loop the counter/pointer increments, the next iteration's scalar address selects and the exit compare now sit before the loop-back
# baseline (speedup 1.0000x reference)
; #define PG8_STAGE(bufoff, gbase, voff) do { _Pragma("unroll") for (int _i = 0; _i < 2; ++_i) \
;         __builtin_amdgcn_global_load_lds((const unsigned*)((const char*)(gbase) + (voff)[_i]), (LAS unsigned*)(lds + (bufoff) + ldsw + _i * 8192), 16, 0, 0); } while (0)
; #define PG8_LDA(dst, b, h) do { _Pragma("unroll") for (int m = 0; m < 4; ++m) _Pragma("unroll") for (int k = 0; k < 2; ++k) dst[m][k] = *(const LAS bf16x8*)(lds + PG8_SA(b, h) + aoff + m * 2048 + k * 1024); } while (0)
; #define PG8_LDB(dst, b, h) do { _Pragma("unroll") for (int n = 0; n < 2; ++n) _Pragma("unroll") for (int k = 0; k < 2; ++k) dst[n][k] = *(const LAS bf16x8*)(lds + PG8_SB(b, h) + boff + n * 2048 + k * 1024); } while (0)
; #define PG8_MMA(ai, bj, At, Bt) do { __builtin_amdgcn_s_setprio(1); _Pragma("unroll") for (int m = 0; m < 4; ++m) _Pragma("unroll") for (int n = 0; n < 2; ++n) _Pragma("unroll") for (int k = 0; k < 2; ++k) \
;         acc[ai][bj][m][n] = __builtin_amdgcn_mfma_f32_16x16x32_bf16(Bt[n][k], At[m][k], acc[ai][bj][m][n], 0, 0, 0); __builtin_amdgcn_s_setprio(0); } while (0)
; #define PG8_WAIT_V(n) asm volatile("s_waitcnt vmcnt(" #n ")" ::: "memory")
; #define PG8_WAIT_L(n) asm volatile("s_waitcnt lgkmcnt(" #n ")" ::: "memory")
; #define PG8_BAR __builtin_amdgcn_s_barrier()
; #define PG8_SCHED __builtin_amdgcn_sched_barrier(0)
; template <class Epi, class Sched>
; __device__ __forceinline__ void gemm_phase(LAS unsigned char* lds, const Gemm g, const Sched& S, const Epi& E) {
;     ...
;             PG8_LDB(B0, 0, 0); PG8_LDB(B1, 0, 1); PG8_SCHED; PG8_LDA(At, 0, 0); PG8_STAGE(PG8_SA(1, 1), a1 + hstepA, voffA);
;             PG8_WAIT_V(8); PG8_WAIT_L(0); PG8_BAR; PG8_MMA(0, 0, At, B0); PG8_MMA(0, 1, At, B1); PG8_BAR; PG8_SCHED;
;             PG8_LDA(At, 0, 1); PG8_STAGE(PG8_SB(0, 0), b2, voffB); PG8_STAGE(PG8_SB(0, 1), b2 + hstepB, voffB); PG8_STAGE(PG8_SA(0, 0), a2, voffA);
;             PG8_WAIT_V(8); PG8_WAIT_L(0); PG8_BAR; PG8_MMA(1, 0, At, B0); PG8_MMA(1, 1, At, B1); PG8_BAR; PG8_SCHED;
.Lprio_gu:
	s_add_u32 s0, s44, 0xfffc0080
	s_addc_u32 s6, s45, -1
	s_add_i32 s26, 0, 0x10000
	s_cmp_eq_u32 s55, 12
	s_cselect_b32 s15, s23, s6
	s_cselect_b32 s14, s53, s0
	v_add_u32_e32 v153, s26, v148
	s_cselect_b32 s7, s19, s47
	s_cselect_b32 s6, s54, s46
	s_add_i32 s0, 0, 0x14000
	ds_read_b128 v[142:145], v153
	ds_read_b128 v[154:157], v153 offset:1024
	ds_read_b128 v[162:165], v153 offset:2048
	ds_read_b128 v[166:169], v153 offset:3072
	v_add_u32_e32 v153, s0, v148
	ds_read_b128 v[170:173], v153
	ds_read_b128 v[174:177], v153 offset:1024
	ds_read_b128 v[190:193], v153 offset:2048
	ds_read_b128 v[196:199], v153 offset:3072
	v_lshl_add_u64 v[158:159], s[44:45], 0, v[138:139]
	s_add_i32 m0, s49, 0xc000
	ds_read_b128 v[200:203], v152
	ds_read_b128 v[204:207], v152 offset:1024
	ds_read_b128 v[208:211], v152 offset:2048
	ds_read_b128 v[212:215], v152 offset:3072
	ds_read_b128 v[216:219], v152 offset:4096
	ds_read_b128 v[220:223], v152 offset:5120
	ds_read_b128 v[224:227], v152 offset:6144
	ds_read_b128 v[228:231], v152 offset:7168
	global_load_lds_dwordx4 v[158:159], off
	v_lshl_add_u64 v[158:159], s[44:45], 0, v[140:141]
	s_add_i32 m0, s49, 0xe000
	s_nop 0
	global_load_lds_dwordx4 v[158:159], off
	s_waitcnt vmcnt(8)
	s_waitcnt lgkmcnt(0)
	s_barrier
	s_waitcnt lgkmcnt(0)
	v_mfma_f32_16x16x32_bf16 v[128:131], v[142:145], v[200:203], 0
	v_mfma_f32_16x16x32_bf16 v[124:127], v[162:165], v[200:203], 0
	v_mfma_f32_16x16x32_bf16 v[112:115], v[142:145], v[208:211], 0
	v_mfma_f32_16x16x32_bf16 v[108:111], v[162:165], v[208:211], 0
	v_mfma_f32_16x16x32_bf16 v[96:99], v[142:145], v[216:219], 0
	v_mfma_f32_16x16x32_bf16 v[92:95], v[162:165], v[216:219], 0
	v_mfma_f32_16x16x32_bf16 v[80:83], v[142:145], v[224:227], 0
	v_mfma_f32_16x16x32_bf16 v[76:79], v[162:165], v[224:227], 0
	v_mfma_f32_16x16x32_bf16 v[128:131], v[154:157], v[204:207], v[128:131]
	v_mfma_f32_16x16x32_bf16 v[124:127], v[166:169], v[204:207], v[124:127]
	v_mfma_f32_16x16x32_bf16 v[112:115], v[154:157], v[212:215], v[112:115]
	v_mfma_f32_16x16x32_bf16 v[108:111], v[166:169], v[212:215], v[108:111]
	v_mfma_f32_16x16x32_bf16 v[96:99], v[154:157], v[220:223], v[96:99]
	v_mfma_f32_16x16x32_bf16 v[92:95], v[166:169], v[220:223], v[92:95]
	v_mfma_f32_16x16x32_bf16 v[80:83], v[154:157], v[228:231], v[80:83]
	v_mfma_f32_16x16x32_bf16 v[76:79], v[166:169], v[228:231], v[76:79]
	v_mfma_f32_16x16x32_bf16 v[120:123], v[170:173], v[200:203], 0
	v_mfma_f32_16x16x32_bf16 v[116:119], v[190:193], v[200:203], 0
	v_mfma_f32_16x16x32_bf16 v[104:107], v[170:173], v[208:211], 0
	v_mfma_f32_16x16x32_bf16 v[100:103], v[190:193], v[208:211], 0
	v_mfma_f32_16x16x32_bf16 v[88:91], v[170:173], v[216:219], 0
	v_mfma_f32_16x16x32_bf16 v[84:87], v[190:193], v[216:219], 0
	v_mfma_f32_16x16x32_bf16 v[72:75], v[170:173], v[224:227], 0
	v_mfma_f32_16x16x32_bf16 v[68:71], v[190:193], v[224:227], 0
	v_mfma_f32_16x16x32_bf16 v[120:123], v[174:177], v[204:207], v[120:123]
	v_mfma_f32_16x16x32_bf16 v[116:119], v[196:199], v[204:207], v[116:119]
	v_mfma_f32_16x16x32_bf16 v[104:107], v[174:177], v[212:215], v[104:107]
	v_mfma_f32_16x16x32_bf16 v[100:103], v[196:199], v[212:215], v[100:103]
	v_mfma_f32_16x16x32_bf16 v[88:91], v[174:177], v[220:223], v[88:91]
	v_mfma_f32_16x16x32_bf16 v[84:87], v[196:199], v[220:223], v[84:87]
	v_mfma_f32_16x16x32_bf16 v[72:75], v[174:177], v[228:231], v[72:75]
	v_mfma_f32_16x16x32_bf16 v[68:71], v[196:199], v[228:231], v[68:71]
	s_barrier
	s_add_i32 s26, s26, s20
	v_lshl_add_u64 v[158:159], s[6:7], 0, v[160:161]
	s_mov_b32 m0, s26
	ds_read_b128 v[200:203], v152 offset:16384
	ds_read_b128 v[204:207], v152 offset:17408
	ds_read_b128 v[208:211], v152 offset:18432
	ds_read_b128 v[212:215], v152 offset:19456
	ds_read_b128 v[216:219], v152 offset:20480
	ds_read_b128 v[220:223], v152 offset:21504
	ds_read_b128 v[224:227], v152 offset:22528
	ds_read_b128 v[228:231], v152 offset:23552
	global_load_lds_dwordx4 v[158:159], off
	s_add_i32 m0, s26, 0x2000
	s_add_u32 s56, s6, 0x40000
	v_lshl_add_u64 v[232:233], s[6:7], 0, v[136:137]
	s_addc_u32 s57, s7, 0
	s_add_i32 s0, s0, s20
	global_load_lds_dwordx4 v[232:233], off
	v_lshl_add_u64 v[234:235], s[56:57], 0, v[160:161]
	s_mov_b32 m0, s0
	v_lshl_add_u64 v[236:237], s[14:15], 0, v[134:135]
	global_load_lds_dwordx4 v[234:235], off
	v_lshl_add_u64 v[234:235], s[56:57], 0, v[136:137]
	s_add_i32 m0, s0, 0x2000
	s_nop 0
	global_load_lds_dwordx4 v[234:235], off
	v_lshl_add_u64 v[234:235], s[14:15], 0, v[132:133]
	s_mov_b32 m0, s49
	s_nop 0
	global_load_lds_dwordx4 v[234:235], off
	s_mov_b32 m0, s50
	s_nop 0
	global_load_lds_dwordx4 v[236:237], off
	s_waitcnt vmcnt(8)
	s_waitcnt lgkmcnt(0)
	s_barrier
; #define PG8_STAGE(bufoff, gbase, voff) do { _Pragma("unroll") for (int _i = 0; _i < 2; ++_i) \
;         __builtin_amdgcn_global_load_lds((const unsigned*)((const char*)(gbase) + (voff)[_i]), (LAS unsigned*)(lds + (bufoff) + ldsw + _i * 8192), 16, 0, 0); } while (0)
; #define PG8_LDA(dst, b, h) do { _Pragma("unroll") for (int m = 0; m < 4; ++m) _Pragma("unroll") for (int k = 0; k < 2; ++k) dst[m][k] = *(const LAS bf16x8*)(lds + PG8_SA(b, h) + aoff + m * 2048 + k * 1024); } while (0)
; #define PG8_LDB(dst, b, h) do { _Pragma("unroll") for (int n = 0; n < 2; ++n) _Pragma("unroll") for (int k = 0; k < 2; ++k) dst[n][k] = *(const LAS bf16x8*)(lds + PG8_SB(b, h) + boff + n * 2048 + k * 1024); } while (0)
; #define PG8_MMA(ai, bj, At, Bt) do { __builtin_amdgcn_s_setprio(1); _Pragma("unroll") for (int m = 0; m < 4; ++m) _Pragma("unroll") for (int n = 0; n < 2; ++n) _Pragma("unroll") for (int k = 0; k < 2; ++k) \
;         acc[ai][bj][m][n] = __builtin_amdgcn_mfma_f32_16x16x32_bf16(Bt[n][k], At[m][k], acc[ai][bj][m][n], 0, 0, 0); __builtin_amdgcn_s_setprio(0); } while (0)
; #define PG8_WAIT_V(n) asm volatile("s_waitcnt vmcnt(" #n ")" ::: "memory")
; #define PG8_WAIT_L(n) asm volatile("s_waitcnt lgkmcnt(" #n ")" ::: "memory")
; #define PG8_BAR __builtin_amdgcn_s_barrier()
; #define PG8_SCHED __builtin_amdgcn_sched_barrier(0)
; template <class Epi, class Sched>
; __device__ __forceinline__ void gemm_phase(LAS unsigned char* lds, const Gemm g, const Sched& S, const Epi& E) {
;     ...
;             PG8_WAIT_V(8); PG8_WAIT_L(0); PG8_BAR; PG8_MMA(1, 0, At, B0); PG8_MMA(1, 1, At, B1); PG8_BAR; PG8_SCHED;
;             PG8_LDB(B0, 1, 0); PG8_LDB(B1, 1, 1); PG8_SCHED; PG8_LDA(At, 1, 0); PG8_STAGE(PG8_SA(0, 1), a2 + hstepA, voffA);
;             PG8_WAIT_V(8); PG8_WAIT_L(0); PG8_BAR; PG8_MMA(0, 0, At, B0); PG8_MMA(0, 1, At, B1); PG8_BAR; PG8_SCHED;
	s_waitcnt lgkmcnt(0)
	v_mfma_f32_16x16x32_bf16 v[64:67], v[142:145], v[200:203], 0
	v_mfma_f32_16x16x32_bf16 v[60:63], v[162:165], v[200:203], 0
	v_mfma_f32_16x16x32_bf16 v[48:51], v[142:145], v[208:211], 0
	v_mfma_f32_16x16x32_bf16 v[44:47], v[162:165], v[208:211], 0
	v_mfma_f32_16x16x32_bf16 v[32:35], v[142:145], v[216:219], 0
	v_mfma_f32_16x16x32_bf16 v[28:31], v[162:165], v[216:219], 0
	v_mfma_f32_16x16x32_bf16 v[16:19], v[142:145], v[224:227], 0
	v_mfma_f32_16x16x32_bf16 v[12:15], v[162:165], v[224:227], 0
	v_mfma_f32_16x16x32_bf16 v[64:67], v[154:157], v[204:207], v[64:67]
	v_mfma_f32_16x16x32_bf16 v[60:63], v[166:169], v[204:207], v[60:63]
	v_mfma_f32_16x16x32_bf16 v[48:51], v[154:157], v[212:215], v[48:51]
	v_mfma_f32_16x16x32_bf16 v[44:47], v[166:169], v[212:215], v[44:47]
	v_mfma_f32_16x16x32_bf16 v[32:35], v[154:157], v[220:223], v[32:35]
	v_mfma_f32_16x16x32_bf16 v[28:31], v[166:169], v[220:223], v[28:31]
	v_mfma_f32_16x16x32_bf16 v[16:19], v[154:157], v[228:231], v[16:19]
	v_mfma_f32_16x16x32_bf16 v[12:15], v[166:169], v[228:231], v[12:15]
	v_mfma_f32_16x16x32_bf16 v[56:59], v[170:173], v[200:203], 0
	v_mfma_f32_16x16x32_bf16 v[52:55], v[190:193], v[200:203], 0
	v_mfma_f32_16x16x32_bf16 v[40:43], v[170:173], v[208:211], 0
	v_mfma_f32_16x16x32_bf16 v[36:39], v[190:193], v[208:211], 0
	v_mfma_f32_16x16x32_bf16 v[24:27], v[170:173], v[216:219], 0
	v_mfma_f32_16x16x32_bf16 v[20:23], v[190:193], v[216:219], 0
	v_mfma_f32_16x16x32_bf16 v[8:11], v[170:173], v[224:227], 0
	v_mfma_f32_16x16x32_bf16 v[4:7], v[190:193], v[224:227], 0
	v_mfma_f32_16x16x32_bf16 v[56:59], v[174:177], v[204:207], v[56:59]
	v_mfma_f32_16x16x32_bf16 v[52:55], v[196:199], v[204:207], v[52:55]
	v_mfma_f32_16x16x32_bf16 v[40:43], v[174:177], v[212:215], v[40:43]
	v_mfma_f32_16x16x32_bf16 v[36:39], v[196:199], v[212:215], v[36:39]
	v_mfma_f32_16x16x32_bf16 v[24:27], v[174:177], v[220:223], v[24:27]
	v_mfma_f32_16x16x32_bf16 v[20:23], v[196:199], v[220:223], v[20:23]
	v_mfma_f32_16x16x32_bf16 v[8:11], v[174:177], v[228:231], v[8:11]
	v_mfma_f32_16x16x32_bf16 v[4:7], v[196:199], v[228:231], v[4:7]
	s_barrier
	s_add_i32 s0, 0, 0x18000
	v_add_u32_e32 v153, s0, v148
	s_add_i32 s26, 0, 0x1c000
	ds_read_b128 v[142:145], v153
	ds_read_b128 v[154:157], v153 offset:1024
	ds_read_b128 v[162:165], v153 offset:2048
	ds_read_b128 v[166:169], v153 offset:3072
	v_add_u32_e32 v153, s26, v148
	ds_read_b128 v[170:173], v153
	ds_read_b128 v[174:177], v153 offset:1024
	ds_read_b128 v[190:193], v153 offset:2048
	ds_read_b128 v[196:199], v153 offset:3072
	s_add_u32 s14, s14, 0x40000
	s_addc_u32 s15, s15, 0
	s_mov_b32 m0, s51
	v_lshl_add_u64 v[238:239], s[14:15], 0, v[132:133]
	ds_read_b128 v[200:203], v152 offset:32768
	ds_read_b128 v[204:207], v152 offset:33792
	ds_read_b128 v[208:211], v152 offset:34816
	ds_read_b128 v[212:215], v152 offset:35840
	ds_read_b128 v[216:219], v152 offset:36864
	ds_read_b128 v[220:223], v152 offset:37888
	ds_read_b128 v[224:227], v152 offset:38912
	ds_read_b128 v[228:231], v152 offset:39936
	global_load_lds_dwordx4 v[238:239], off
	v_lshl_add_u64 v[238:239], s[14:15], 0, v[134:135]
	s_mov_b32 m0, s52
	s_nop 0
	global_load_lds_dwordx4 v[238:239], off
	s_waitcnt vmcnt(8)
	s_waitcnt lgkmcnt(0)
	s_barrier
	s_waitcnt lgkmcnt(0)
	v_mfma_f32_16x16x32_bf16 v[128:131], v[142:145], v[200:203], v[128:131]
	v_mfma_f32_16x16x32_bf16 v[124:127], v[162:165], v[200:203], v[124:127]
	v_mfma_f32_16x16x32_bf16 v[112:115], v[142:145], v[208:211], v[112:115]
	v_mfma_f32_16x16x32_bf16 v[108:111], v[162:165], v[208:211], v[108:111]
	v_mfma_f32_16x16x32_bf16 v[96:99], v[142:145], v[216:219], v[96:99]
	v_mfma_f32_16x16x32_bf16 v[92:95], v[162:165], v[216:219], v[92:95]
	v_mfma_f32_16x16x32_bf16 v[80:83], v[142:145], v[224:227], v[80:83]
	v_mfma_f32_16x16x32_bf16 v[76:79], v[162:165], v[224:227], v[76:79]
	v_mfma_f32_16x16x32_bf16 v[128:131], v[154:157], v[204:207], v[128:131]
	v_mfma_f32_16x16x32_bf16 v[124:127], v[166:169], v[204:207], v[124:127]
	v_mfma_f32_16x16x32_bf16 v[112:115], v[154:157], v[212:215], v[112:115]
	v_mfma_f32_16x16x32_bf16 v[108:111], v[166:169], v[212:215], v[108:111]
	v_mfma_f32_16x16x32_bf16 v[96:99], v[154:157], v[220:223], v[96:99]
	v_mfma_f32_16x16x32_bf16 v[92:95], v[166:169], v[220:223], v[92:95]
	v_mfma_f32_16x16x32_bf16 v[80:83], v[154:157], v[228:231], v[80:83]
	v_mfma_f32_16x16x32_bf16 v[76:79], v[166:169], v[228:231], v[76:79]
	v_mfma_f32_16x16x32_bf16 v[120:123], v[170:173], v[200:203], v[120:123]
	v_mfma_f32_16x16x32_bf16 v[116:119], v[190:193], v[200:203], v[116:119]
	v_mfma_f32_16x16x32_bf16 v[104:107], v[170:173], v[208:211], v[104:107]
	v_mfma_f32_16x16x32_bf16 v[100:103], v[190:193], v[208:211], v[100:103]
	v_mfma_f32_16x16x32_bf16 v[88:91], v[170:173], v[216:219], v[88:91]
	v_mfma_f32_16x16x32_bf16 v[84:87], v[190:193], v[216:219], v[84:87]
	v_mfma_f32_16x16x32_bf16 v[72:75], v[170:173], v[224:227], v[72:75]
	v_mfma_f32_16x16x32_bf16 v[68:71], v[190:193], v[224:227], v[68:71]
	v_mfma_f32_16x16x32_bf16 v[120:123], v[174:177], v[204:207], v[120:123]
	v_mfma_f32_16x16x32_bf16 v[116:119], v[196:199], v[204:207], v[116:119]
	v_mfma_f32_16x16x32_bf16 v[104:107], v[174:177], v[212:215], v[104:107]
	v_mfma_f32_16x16x32_bf16 v[100:103], v[196:199], v[212:215], v[100:103]
	v_mfma_f32_16x16x32_bf16 v[88:91], v[174:177], v[220:223], v[88:91]
	v_mfma_f32_16x16x32_bf16 v[84:87], v[196:199], v[220:223], v[84:87]
	v_mfma_f32_16x16x32_bf16 v[72:75], v[174:177], v[228:231], v[72:75]
	v_mfma_f32_16x16x32_bf16 v[68:71], v[196:199], v[228:231], v[68:71]
	s_barrier
; #define PG8_STAGE(bufoff, gbase, voff) do { _Pragma("unroll") for (int _i = 0; _i < 2; ++_i) \
;         __builtin_amdgcn_global_load_lds((const unsigned*)((const char*)(gbase) + (voff)[_i]), (LAS unsigned*)(lds + (bufoff) + ldsw + _i * 8192), 16, 0, 0); } while (0)
; #define PG8_LDA(dst, b, h) do { _Pragma("unroll") for (int m = 0; m < 4; ++m) _Pragma("unroll") for (int k = 0; k < 2; ++k) dst[m][k] = *(const LAS bf16x8*)(lds + PG8_SA(b, h) + aoff + m * 2048 + k * 1024); } while (0)
; #define PG8_LDB(dst, b, h) do { _Pragma("unroll") for (int n = 0; n < 2; ++n) _Pragma("unroll") for (int k = 0; k < 2; ++k) dst[n][k] = *(const LAS bf16x8*)(lds + PG8_SB(b, h) + boff + n * 2048 + k * 1024); } while (0)
; #define PG8_MMA(ai, bj, At, Bt) do { __builtin_amdgcn_s_setprio(1); _Pragma("unroll") for (int m = 0; m < 4; ++m) _Pragma("unroll") for (int n = 0; n < 2; ++n) _Pragma("unroll") for (int k = 0; k < 2; ++k) \
;         acc[ai][bj][m][n] = __builtin_amdgcn_mfma_f32_16x16x32_bf16(Bt[n][k], At[m][k], acc[ai][bj][m][n], 0, 0, 0); __builtin_amdgcn_s_setprio(0); } while (0)
; #define PG8_WAIT_V(n) asm volatile("s_waitcnt vmcnt(" #n ")" ::: "memory")
; #define PG8_WAIT_L(n) asm volatile("s_waitcnt lgkmcnt(" #n ")" ::: "memory")
; #define PG8_BAR __builtin_amdgcn_s_barrier()
; #define PG8_SCHED __builtin_amdgcn_sched_barrier(0)
; template <class Epi, class Sched>
; __device__ __forceinline__ void gemm_phase(LAS unsigned char* lds, const Gemm g, const Sched& S, const Epi& E) {
;     ...
;         for (int t = 0; t < nt; t += 2) {
;             const bool last = (t == nt - 2);
;             const char* a1 = cA + (size_t)(t + 1) * kstep;
;             const char* a2 = last ? nA : cA + (size_t)(t + 2) * kstep; const char* b2 = last ? nB : cB + (size_t)(t + 2) * kstep;
;             const char* a3 = a2 + kstep; const char* b3 = b2 + kstep;
;             PG8_LDB(B0, 0, 0); PG8_LDB(B1, 0, 1); PG8_SCHED; PG8_LDA(At, 0, 0); PG8_STAGE(PG8_SA(1, 1), a1 + hstepA, voffA);
;     ...
;             PG8_LDA(At, 1, 1); PG8_STAGE(PG8_SB(1, 0), b3, voffB); PG8_STAGE(PG8_SB(1, 1), b3 + hstepB, voffB); PG8_STAGE(PG8_SA(1, 0), a3, voffA);
;             PG8_WAIT_V(8); PG8_WAIT_L(0); PG8_BAR; PG8_MMA(1, 0, At, B0); PG8_MMA(1, 1, At, B1); PG8_BAR; PG8_SCHED;
	s_add_i32 s0, s0, s20
	v_lshl_add_u64 v[158:159], v[158:159], 0, s[30:31]
	s_mov_b32 m0, s0
	ds_read_b128 v[200:203], v152 offset:49152
	ds_read_b128 v[204:207], v152 offset:50176
	ds_read_b128 v[208:211], v152 offset:51200
	ds_read_b128 v[212:215], v152 offset:52224
	ds_read_b128 v[216:219], v152 offset:53248
	ds_read_b128 v[220:223], v152 offset:54272
	ds_read_b128 v[224:227], v152 offset:55296
	ds_read_b128 v[228:231], v152 offset:56320
	global_load_lds_dwordx4 v[158:159], off
	s_add_i32 m0, s0, 0x2000
	s_add_u32 s6, s6, 0x40080
	v_lshl_add_u64 v[158:159], v[232:233], 0, s[30:31]
	s_addc_u32 s7, s7, 0
	s_add_i32 s0, s26, s20
	global_load_lds_dwordx4 v[158:159], off
	v_lshl_add_u64 v[158:159], s[6:7], 0, v[160:161]
	s_mov_b32 m0, s0
	s_nop 0
	global_load_lds_dwordx4 v[158:159], off
	v_lshl_add_u64 v[158:159], s[6:7], 0, v[136:137]
	s_add_i32 m0, s0, 0x2000
	s_nop 0
	global_load_lds_dwordx4 v[158:159], off
	v_lshl_add_u64 v[158:159], v[234:235], 0, s[30:31]
	s_mov_b32 m0, s24
	s_nop 0
	global_load_lds_dwordx4 v[158:159], off
	v_lshl_add_u64 v[158:159], v[236:237], 0, s[30:31]
	s_mov_b32 m0, s25
	s_nop 0
	global_load_lds_dwordx4 v[158:159], off
	s_waitcnt vmcnt(8)
	s_waitcnt lgkmcnt(0)
	s_barrier
	s_waitcnt lgkmcnt(0)
	v_mfma_f32_16x16x32_bf16 v[64:67], v[142:145], v[200:203], v[64:67]
	v_mfma_f32_16x16x32_bf16 v[60:63], v[162:165], v[200:203], v[60:63]
	v_mfma_f32_16x16x32_bf16 v[48:51], v[142:145], v[208:211], v[48:51]
	v_mfma_f32_16x16x32_bf16 v[44:47], v[162:165], v[208:211], v[44:47]
	v_mfma_f32_16x16x32_bf16 v[32:35], v[142:145], v[216:219], v[32:35]
	v_mfma_f32_16x16x32_bf16 v[28:31], v[162:165], v[216:219], v[28:31]
	v_mfma_f32_16x16x32_bf16 v[16:19], v[142:145], v[224:227], v[16:19]
	v_mfma_f32_16x16x32_bf16 v[12:15], v[162:165], v[224:227], v[12:15]
	v_mfma_f32_16x16x32_bf16 v[64:67], v[154:157], v[204:207], v[64:67]
	v_mfma_f32_16x16x32_bf16 v[60:63], v[166:169], v[204:207], v[60:63]
	v_mfma_f32_16x16x32_bf16 v[48:51], v[154:157], v[212:215], v[48:51]
	v_mfma_f32_16x16x32_bf16 v[44:47], v[166:169], v[212:215], v[44:47]
	v_mfma_f32_16x16x32_bf16 v[32:35], v[154:157], v[220:223], v[32:35]
	v_mfma_f32_16x16x32_bf16 v[28:31], v[166:169], v[220:223], v[28:31]
	v_mfma_f32_16x16x32_bf16 v[16:19], v[154:157], v[228:231], v[16:19]
	v_mfma_f32_16x16x32_bf16 v[12:15], v[166:169], v[228:231], v[12:15]
	v_mfma_f32_16x16x32_bf16 v[56:59], v[170:173], v[200:203], v[56:59]
	v_mfma_f32_16x16x32_bf16 v[52:55], v[190:193], v[200:203], v[52:55]
	v_mfma_f32_16x16x32_bf16 v[40:43], v[170:173], v[208:211], v[40:43]
	v_mfma_f32_16x16x32_bf16 v[36:39], v[190:193], v[208:211], v[36:39]
	v_mfma_f32_16x16x32_bf16 v[24:27], v[170:173], v[216:219], v[24:27]
	v_mfma_f32_16x16x32_bf16 v[20:23], v[190:193], v[216:219], v[20:23]
	v_mfma_f32_16x16x32_bf16 v[8:11], v[170:173], v[224:227], v[8:11]
	v_mfma_f32_16x16x32_bf16 v[4:7], v[190:193], v[224:227], v[4:7]
	v_mfma_f32_16x16x32_bf16 v[56:59], v[174:177], v[204:207], v[56:59]
	v_mfma_f32_16x16x32_bf16 v[52:55], v[196:199], v[204:207], v[52:55]
	v_mfma_f32_16x16x32_bf16 v[40:43], v[174:177], v[212:215], v[40:43]
	v_mfma_f32_16x16x32_bf16 v[36:39], v[196:199], v[212:215], v[36:39]
	v_mfma_f32_16x16x32_bf16 v[24:27], v[174:177], v[220:223], v[24:27]
	v_mfma_f32_16x16x32_bf16 v[20:23], v[196:199], v[220:223], v[20:23]
	v_mfma_f32_16x16x32_bf16 v[8:11], v[174:177], v[228:231], v[8:11]
	v_mfma_f32_16x16x32_bf16 v[4:7], v[196:199], v[228:231], v[4:7]
	s_add_i32 s55, s55, 2
	s_add_u32 s44, s44, 0x100
	s_addc_u32 s45, s45, 0
	s_add_u32 s46, s46, 0x100
	s_addc_u32 s47, s47, 0
	s_add_u32 s0, s44, 0xfffc0080
	s_addc_u32 s6, s45, -1
	s_add_i32 s26, 0, 0x10000
	s_cmp_eq_u32 s55, 12
	s_cselect_b32 s15, s23, s6
	s_cselect_b32 s14, s53, s0
	v_add_u32_e32 v153, s26, v148
	s_cselect_b32 s7, s19, s47
	s_cselect_b32 s6, s54, s46
	s_add_i32 s0, 0, 0x14000
	s_cmp_gt_u32 s55, 13
	s_barrier
.LBB0_718:
	ds_read_b128 v[142:145], v153
	ds_read_b128 v[154:157], v153 offset:1024
	ds_read_b128 v[162:165], v153 offset:2048
	ds_read_b128 v[166:169], v153 offset:3072
	v_add_u32_e32 v153, s0, v148
	ds_read_b128 v[170:173], v153
	ds_read_b128 v[174:177], v153 offset:1024
	ds_read_b128 v[190:193], v153 offset:2048
	ds_read_b128 v[196:199], v153 offset:3072
	v_lshl_add_u64 v[158:159], s[44:45], 0, v[138:139]
	s_add_i32 m0, s49, 0xc000
	ds_read_b128 v[200:203], v152
	ds_read_b128 v[204:207], v152 offset:1024
	ds_read_b128 v[208:211], v152 offset:2048
	ds_read_b128 v[212:215], v152 offset:3072
	ds_read_b128 v[216:219], v152 offset:4096
	ds_read_b128 v[220:223], v152 offset:5120
	ds_read_b128 v[224:227], v152 offset:6144
	ds_read_b128 v[228:231], v152 offset:7168
	global_load_lds_dwordx4 v[158:159], off
	v_lshl_add_u64 v[158:159], s[44:45], 0, v[140:141]
	s_add_i32 m0, s49, 0xe000
	s_nop 0
	global_load_lds_dwordx4 v[158:159], off
	s_waitcnt vmcnt(8)
	s_waitcnt lgkmcnt(0)
	s_barrier
; #define PG8_STAGE(bufoff, gbase, voff) do { _Pragma("unroll") for (int _i = 0; _i < 2; ++_i) \
;         __builtin_amdgcn_global_load_lds((const unsigned*)((const char*)(gbase) + (voff)[_i]), (LAS unsigned*)(lds + (bufoff) + ldsw + _i * 8192), 16, 0, 0); } while (0)
; #define PG8_LDA(dst, b, h) do { _Pragma("unroll") for (int m = 0; m < 4; ++m) _Pragma("unroll") for (int k = 0; k < 2; ++k) dst[m][k] = *(const LAS bf16x8*)(lds + PG8_SA(b, h) + aoff + m * 2048 + k * 1024); } while (0)
; #define PG8_LDB(dst, b, h) do { _Pragma("unroll") for (int n = 0; n < 2; ++n) _Pragma("unroll") for (int k = 0; k < 2; ++k) dst[n][k] = *(const LAS bf16x8*)(lds + PG8_SB(b, h) + boff + n * 2048 + k * 1024); } while (0)
; #define PG8_MMA(ai, bj, At, Bt) do { __builtin_amdgcn_s_setprio(1); _Pragma("unroll") for (int m = 0; m < 4; ++m) _Pragma("unroll") for (int n = 0; n < 2; ++n) _Pragma("unroll") for (int k = 0; k < 2; ++k) \
;         acc[ai][bj][m][n] = __builtin_amdgcn_mfma_f32_16x16x32_bf16(Bt[n][k], At[m][k], acc[ai][bj][m][n], 0, 0, 0); __builtin_amdgcn_s_setprio(0); } while (0)
; #define PG8_WAIT_V(n) asm volatile("s_waitcnt vmcnt(" #n ")" ::: "memory")
; #define PG8_WAIT_L(n) asm volatile("s_waitcnt lgkmcnt(" #n ")" ::: "memory")
; #define PG8_BAR __builtin_amdgcn_s_barrier()
; #define PG8_SCHED __builtin_amdgcn_sched_barrier(0)
; template <class Epi, class Sched>
; __device__ __forceinline__ void gemm_phase(LAS unsigned char* lds, const Gemm g, const Sched& S, const Epi& E) {
;     ...
;             PG8_WAIT_V(8); PG8_WAIT_L(0); PG8_BAR; PG8_MMA(0, 0, At, B0); PG8_MMA(0, 1, At, B1); PG8_BAR; PG8_SCHED;
;             PG8_LDA(At, 0, 1); PG8_STAGE(PG8_SB(0, 0), b2, voffB); PG8_STAGE(PG8_SB(0, 1), b2 + hstepB, voffB); PG8_STAGE(PG8_SA(0, 0), a2, voffA);
;             PG8_WAIT_V(8); PG8_WAIT_L(0); PG8_BAR; PG8_MMA(1, 0, At, B0); PG8_MMA(1, 1, At, B1); PG8_BAR; PG8_SCHED;
;             PG8_LDB(B0, 1, 0); PG8_LDB(B1, 1, 1); PG8_SCHED; PG8_LDA(At, 1, 0); PG8_STAGE(PG8_SA(0, 1), a2 + hstepA, voffA);
;             PG8_WAIT_V(8); PG8_WAIT_L(0); PG8_BAR; PG8_MMA(0, 0, At, B0); PG8_MMA(0, 1, At, B1); PG8_BAR; PG8_SCHED;
	s_waitcnt lgkmcnt(0)
	v_mfma_f32_16x16x32_bf16 v[128:131], v[142:145], v[200:203], v[128:131]
	v_mfma_f32_16x16x32_bf16 v[124:127], v[162:165], v[200:203], v[124:127]
	v_mfma_f32_16x16x32_bf16 v[112:115], v[142:145], v[208:211], v[112:115]
	v_mfma_f32_16x16x32_bf16 v[108:111], v[162:165], v[208:211], v[108:111]
	v_mfma_f32_16x16x32_bf16 v[96:99], v[142:145], v[216:219], v[96:99]
	v_mfma_f32_16x16x32_bf16 v[92:95], v[162:165], v[216:219], v[92:95]
	v_mfma_f32_16x16x32_bf16 v[80:83], v[142:145], v[224:227], v[80:83]
	v_mfma_f32_16x16x32_bf16 v[76:79], v[162:165], v[224:227], v[76:79]
	v_mfma_f32_16x16x32_bf16 v[128:131], v[154:157], v[204:207], v[128:131]
	v_mfma_f32_16x16x32_bf16 v[124:127], v[166:169], v[204:207], v[124:127]
	v_mfma_f32_16x16x32_bf16 v[112:115], v[154:157], v[212:215], v[112:115]
	v_mfma_f32_16x16x32_bf16 v[108:111], v[166:169], v[212:215], v[108:111]
	v_mfma_f32_16x16x32_bf16 v[96:99], v[154:157], v[220:223], v[96:99]
	v_mfma_f32_16x16x32_bf16 v[92:95], v[166:169], v[220:223], v[92:95]
	v_mfma_f32_16x16x32_bf16 v[80:83], v[154:157], v[228:231], v[80:83]
	v_mfma_f32_16x16x32_bf16 v[76:79], v[166:169], v[228:231], v[76:79]
	v_mfma_f32_16x16x32_bf16 v[120:123], v[170:173], v[200:203], v[120:123]
	v_mfma_f32_16x16x32_bf16 v[116:119], v[190:193], v[200:203], v[116:119]
	v_mfma_f32_16x16x32_bf16 v[104:107], v[170:173], v[208:211], v[104:107]
	v_mfma_f32_16x16x32_bf16 v[100:103], v[190:193], v[208:211], v[100:103]
	v_mfma_f32_16x16x32_bf16 v[88:91], v[170:173], v[216:219], v[88:91]
	v_mfma_f32_16x16x32_bf16 v[84:87], v[190:193], v[216:219], v[84:87]
	v_mfma_f32_16x16x32_bf16 v[72:75], v[170:173], v[224:227], v[72:75]
	v_mfma_f32_16x16x32_bf16 v[68:71], v[190:193], v[224:227], v[68:71]
	v_mfma_f32_16x16x32_bf16 v[120:123], v[174:177], v[204:207], v[120:123]
	v_mfma_f32_16x16x32_bf16 v[116:119], v[196:199], v[204:207], v[116:119]
	v_mfma_f32_16x16x32_bf16 v[104:107], v[174:177], v[212:215], v[104:107]
	v_mfma_f32_16x16x32_bf16 v[100:103], v[196:199], v[212:215], v[100:103]
	v_mfma_f32_16x16x32_bf16 v[88:91], v[174:177], v[220:223], v[88:91]
	v_mfma_f32_16x16x32_bf16 v[84:87], v[196:199], v[220:223], v[84:87]
	v_mfma_f32_16x16x32_bf16 v[72:75], v[174:177], v[228:231], v[72:75]
	v_mfma_f32_16x16x32_bf16 v[68:71], v[196:199], v[228:231], v[68:71]
	s_barrier
	s_add_i32 s26, s26, s20
	v_lshl_add_u64 v[158:159], s[6:7], 0, v[160:161]
	s_mov_b32 m0, s26
	ds_read_b128 v[200:203], v152 offset:16384
	ds_read_b128 v[204:207], v152 offset:17408
	ds_read_b128 v[208:211], v152 offset:18432
	ds_read_b128 v[212:215], v152 offset:19456
	ds_read_b128 v[216:219], v152 offset:20480
	ds_read_b128 v[220:223], v152 offset:21504
	ds_read_b128 v[224:227], v152 offset:22528
	ds_read_b128 v[228:231], v152 offset:23552
	global_load_lds_dwordx4 v[158:159], off
	s_add_i32 m0, s26, 0x2000
	s_add_u32 s56, s6, 0x40000
	v_lshl_add_u64 v[232:233], s[6:7], 0, v[136:137]
	s_addc_u32 s57, s7, 0
	s_add_i32 s0, s0, s20
	global_load_lds_dwordx4 v[232:233], off
	v_lshl_add_u64 v[234:235], s[56:57], 0, v[160:161]
	s_mov_b32 m0, s0
	v_lshl_add_u64 v[236:237], s[14:15], 0, v[134:135]
	global_load_lds_dwordx4 v[234:235], off
	v_lshl_add_u64 v[234:235], s[56:57], 0, v[136:137]
	s_add_i32 m0, s0, 0x2000
	s_nop 0
	global_load_lds_dwordx4 v[234:235], off
	v_lshl_add_u64 v[234:235], s[14:15], 0, v[132:133]
	s_mov_b32 m0, s49
	s_nop 0
	global_load_lds_dwordx4 v[234:235], off
	s_mov_b32 m0, s50
	s_nop 0
	global_load_lds_dwordx4 v[236:237], off
	s_waitcnt vmcnt(8)
	s_waitcnt lgkmcnt(0)
	s_barrier
	s_waitcnt lgkmcnt(0)
	v_mfma_f32_16x16x32_bf16 v[64:67], v[142:145], v[200:203], v[64:67]
	v_mfma_f32_16x16x32_bf16 v[60:63], v[162:165], v[200:203], v[60:63]
	v_mfma_f32_16x16x32_bf16 v[48:51], v[142:145], v[208:211], v[48:51]
	v_mfma_f32_16x16x32_bf16 v[44:47], v[162:165], v[208:211], v[44:47]
	v_mfma_f32_16x16x32_bf16 v[32:35], v[142:145], v[216:219], v[32:35]
	v_mfma_f32_16x16x32_bf16 v[28:31], v[162:165], v[216:219], v[28:31]
	v_mfma_f32_16x16x32_bf16 v[16:19], v[142:145], v[224:227], v[16:19]
	v_mfma_f32_16x16x32_bf16 v[12:15], v[162:165], v[224:227], v[12:15]
	v_mfma_f32_16x16x32_bf16 v[64:67], v[154:157], v[204:207], v[64:67]
	v_mfma_f32_16x16x32_bf16 v[60:63], v[166:169], v[204:207], v[60:63]
	v_mfma_f32_16x16x32_bf16 v[48:51], v[154:157], v[212:215], v[48:51]
	v_mfma_f32_16x16x32_bf16 v[44:47], v[166:169], v[212:215], v[44:47]
	v_mfma_f32_16x16x32_bf16 v[32:35], v[154:157], v[220:223], v[32:35]
	v_mfma_f32_16x16x32_bf16 v[28:31], v[166:169], v[220:223], v[28:31]
	v_mfma_f32_16x16x32_bf16 v[16:19], v[154:157], v[228:231], v[16:19]
	v_mfma_f32_16x16x32_bf16 v[12:15], v[166:169], v[228:231], v[12:15]
	v_mfma_f32_16x16x32_bf16 v[56:59], v[170:173], v[200:203], v[56:59]
	v_mfma_f32_16x16x32_bf16 v[52:55], v[190:193], v[200:203], v[52:55]
	v_mfma_f32_16x16x32_bf16 v[40:43], v[170:173], v[208:211], v[40:43]
	v_mfma_f32_16x16x32_bf16 v[36:39], v[190:193], v[208:211], v[36:39]
	v_mfma_f32_16x16x32_bf16 v[24:27], v[170:173], v[216:219], v[24:27]
	v_mfma_f32_16x16x32_bf16 v[20:23], v[190:193], v[216:219], v[20:23]
	v_mfma_f32_16x16x32_bf16 v[8:11], v[170:173], v[224:227], v[8:11]
	v_mfma_f32_16x16x32_bf16 v[4:7], v[190:193], v[224:227], v[4:7]
	v_mfma_f32_16x16x32_bf16 v[56:59], v[174:177], v[204:207], v[56:59]
	v_mfma_f32_16x16x32_bf16 v[52:55], v[196:199], v[204:207], v[52:55]
	v_mfma_f32_16x16x32_bf16 v[40:43], v[174:177], v[212:215], v[40:43]
	v_mfma_f32_16x16x32_bf16 v[36:39], v[196:199], v[212:215], v[36:39]
	v_mfma_f32_16x16x32_bf16 v[24:27], v[174:177], v[220:223], v[24:27]
	v_mfma_f32_16x16x32_bf16 v[20:23], v[196:199], v[220:223], v[20:23]
	v_mfma_f32_16x16x32_bf16 v[8:11], v[174:177], v[228:231], v[8:11]
	v_mfma_f32_16x16x32_bf16 v[4:7], v[196:199], v[228:231], v[4:7]
	s_barrier
; #define PG8_STAGE(bufoff, gbase, voff) do { _Pragma("unroll") for (int _i = 0; _i < 2; ++_i) \
;         __builtin_amdgcn_global_load_lds((const unsigned*)((const char*)(gbase) + (voff)[_i]), (LAS unsigned*)(lds + (bufoff) + ldsw + _i * 8192), 16, 0, 0); } while (0)
; #define PG8_LDA(dst, b, h) do { _Pragma("unroll") for (int m = 0; m < 4; ++m) _Pragma("unroll") for (int k = 0; k < 2; ++k) dst[m][k] = *(const LAS bf16x8*)(lds + PG8_SA(b, h) + aoff + m * 2048 + k * 1024); } while (0)
; #define PG8_LDB(dst, b, h) do { _Pragma("unroll") for (int n = 0; n < 2; ++n) _Pragma("unroll") for (int k = 0; k < 2; ++k) dst[n][k] = *(const LAS bf16x8*)(lds + PG8_SB(b, h) + boff + n * 2048 + k * 1024); } while (0)
; #define PG8_MMA(ai, bj, At, Bt) do { __builtin_amdgcn_s_setprio(1); _Pragma("unroll") for (int m = 0; m < 4; ++m) _Pragma("unroll") for (int n = 0; n < 2; ++n) _Pragma("unroll") for (int k = 0; k < 2; ++k) \
;         acc[ai][bj][m][n] = __builtin_amdgcn_mfma_f32_16x16x32_bf16(Bt[n][k], At[m][k], acc[ai][bj][m][n], 0, 0, 0); __builtin_amdgcn_s_setprio(0); } while (0)
; #define PG8_WAIT_V(n) asm volatile("s_waitcnt vmcnt(" #n ")" ::: "memory")
; #define PG8_WAIT_L(n) asm volatile("s_waitcnt lgkmcnt(" #n ")" ::: "memory")
; #define PG8_BAR __builtin_amdgcn_s_barrier()
; #define PG8_SCHED __builtin_amdgcn_sched_barrier(0)
; template <class Epi, class Sched>
; __device__ __forceinline__ void gemm_phase(LAS unsigned char* lds, const Gemm g, const Sched& S, const Epi& E) {
;     ...
;             PG8_LDB(B0, 1, 0); PG8_LDB(B1, 1, 1); PG8_SCHED; PG8_LDA(At, 1, 0); PG8_STAGE(PG8_SA(0, 1), a2 + hstepA, voffA);
;             PG8_WAIT_V(8); PG8_WAIT_L(0); PG8_BAR; PG8_MMA(0, 0, At, B0); PG8_MMA(0, 1, At, B1); PG8_BAR; PG8_SCHED;
	s_add_i32 s0, 0, 0x18000
	v_add_u32_e32 v153, s0, v148
	s_add_i32 s26, 0, 0x1c000
	ds_read_b128 v[142:145], v153
	ds_read_b128 v[154:157], v153 offset:1024
	ds_read_b128 v[162:165], v153 offset:2048
	ds_read_b128 v[166:169], v153 offset:3072
	v_add_u32_e32 v153, s26, v148
	ds_read_b128 v[170:173], v153
	ds_read_b128 v[174:177], v153 offset:1024
	ds_read_b128 v[190:193], v153 offset:2048
	ds_read_b128 v[196:199], v153 offset:3072
	s_add_u32 s14, s14, 0x40000
	s_addc_u32 s15, s15, 0
	s_mov_b32 m0, s51
	v_lshl_add_u64 v[238:239], s[14:15], 0, v[132:133]
	ds_read_b128 v[200:203], v152 offset:32768
	ds_read_b128 v[204:207], v152 offset:33792
	ds_read_b128 v[208:211], v152 offset:34816
	ds_read_b128 v[212:215], v152 offset:35840
	ds_read_b128 v[216:219], v152 offset:36864
	ds_read_b128 v[220:223], v152 offset:37888
	ds_read_b128 v[224:227], v152 offset:38912
	ds_read_b128 v[228:231], v152 offset:39936
	global_load_lds_dwordx4 v[238:239], off
	v_lshl_add_u64 v[238:239], s[14:15], 0, v[134:135]
	s_mov_b32 m0, s52
	s_nop 0
	global_load_lds_dwordx4 v[238:239], off
	s_waitcnt vmcnt(8)
	s_waitcnt lgkmcnt(0)
	s_barrier
	s_waitcnt lgkmcnt(0)
	v_mfma_f32_16x16x32_bf16 v[128:131], v[142:145], v[200:203], v[128:131]
	v_mfma_f32_16x16x32_bf16 v[124:127], v[162:165], v[200:203], v[124:127]
	v_mfma_f32_16x16x32_bf16 v[112:115], v[142:145], v[208:211], v[112:115]
	v_mfma_f32_16x16x32_bf16 v[108:111], v[162:165], v[208:211], v[108:111]
	v_mfma_f32_16x16x32_bf16 v[96:99], v[142:145], v[216:219], v[96:99]
	v_mfma_f32_16x16x32_bf16 v[92:95], v[162:165], v[216:219], v[92:95]
	v_mfma_f32_16x16x32_bf16 v[80:83], v[142:145], v[224:227], v[80:83]
	v_mfma_f32_16x16x32_bf16 v[76:79], v[162:165], v[224:227], v[76:79]
	v_mfma_f32_16x16x32_bf16 v[128:131], v[154:157], v[204:207], v[128:131]
	v_mfma_f32_16x16x32_bf16 v[124:127], v[166:169], v[204:207], v[124:127]
	v_mfma_f32_16x16x32_bf16 v[112:115], v[154:157], v[212:215], v[112:115]
	v_mfma_f32_16x16x32_bf16 v[108:111], v[166:169], v[212:215], v[108:111]
	v_mfma_f32_16x16x32_bf16 v[96:99], v[154:157], v[220:223], v[96:99]
	v_mfma_f32_16x16x32_bf16 v[92:95], v[166:169], v[220:223], v[92:95]
	v_mfma_f32_16x16x32_bf16 v[80:83], v[154:157], v[228:231], v[80:83]
	v_mfma_f32_16x16x32_bf16 v[76:79], v[166:169], v[228:231], v[76:79]
	v_mfma_f32_16x16x32_bf16 v[120:123], v[170:173], v[200:203], v[120:123]
	v_mfma_f32_16x16x32_bf16 v[116:119], v[190:193], v[200:203], v[116:119]
	v_mfma_f32_16x16x32_bf16 v[104:107], v[170:173], v[208:211], v[104:107]
	v_mfma_f32_16x16x32_bf16 v[100:103], v[190:193], v[208:211], v[100:103]
	v_mfma_f32_16x16x32_bf16 v[88:91], v[170:173], v[216:219], v[88:91]
	v_mfma_f32_16x16x32_bf16 v[84:87], v[190:193], v[216:219], v[84:87]
	v_mfma_f32_16x16x32_bf16 v[72:75], v[170:173], v[224:227], v[72:75]
	v_mfma_f32_16x16x32_bf16 v[68:71], v[190:193], v[224:227], v[68:71]
	v_mfma_f32_16x16x32_bf16 v[120:123], v[174:177], v[204:207], v[120:123]
	v_mfma_f32_16x16x32_bf16 v[116:119], v[196:199], v[204:207], v[116:119]
	v_mfma_f32_16x16x32_bf16 v[104:107], v[174:177], v[212:215], v[104:107]
	v_mfma_f32_16x16x32_bf16 v[100:103], v[196:199], v[212:215], v[100:103]
	v_mfma_f32_16x16x32_bf16 v[88:91], v[174:177], v[220:223], v[88:91]
	v_mfma_f32_16x16x32_bf16 v[84:87], v[196:199], v[220:223], v[84:87]
	v_mfma_f32_16x16x32_bf16 v[72:75], v[174:177], v[228:231], v[72:75]
	v_mfma_f32_16x16x32_bf16 v[68:71], v[196:199], v[228:231], v[68:71]
	s_barrier
; #define PG8_STAGE(bufoff, gbase, voff) do { _Pragma("unroll") for (int _i = 0; _i < 2; ++_i) \
;         __builtin_amdgcn_global_load_lds((const unsigned*)((const char*)(gbase) + (voff)[_i]), (LAS unsigned*)(lds + (bufoff) + ldsw + _i * 8192), 16, 0, 0); } while (0)
; #define PG8_LDA(dst, b, h) do { _Pragma("unroll") for (int m = 0; m < 4; ++m) _Pragma("unroll") for (int k = 0; k < 2; ++k) dst[m][k] = *(const LAS bf16x8*)(lds + PG8_SA(b, h) + aoff + m * 2048 + k * 1024); } while (0)
; #define PG8_LDB(dst, b, h) do { _Pragma("unroll") for (int n = 0; n < 2; ++n) _Pragma("unroll") for (int k = 0; k < 2; ++k) dst[n][k] = *(const LAS bf16x8*)(lds + PG8_SB(b, h) + boff + n * 2048 + k * 1024); } while (0)
; #define PG8_MMA(ai, bj, At, Bt) do { __builtin_amdgcn_s_setprio(1); _Pragma("unroll") for (int m = 0; m < 4; ++m) _Pragma("unroll") for (int n = 0; n < 2; ++n) _Pragma("unroll") for (int k = 0; k < 2; ++k) \
;         acc[ai][bj][m][n] = __builtin_amdgcn_mfma_f32_16x16x32_bf16(Bt[n][k], At[m][k], acc[ai][bj][m][n], 0, 0, 0); __builtin_amdgcn_s_setprio(0); } while (0)
; #define PG8_WAIT_V(n) asm volatile("s_waitcnt vmcnt(" #n ")" ::: "memory")
; #define PG8_WAIT_L(n) asm volatile("s_waitcnt lgkmcnt(" #n ")" ::: "memory")
; #define PG8_BAR __builtin_amdgcn_s_barrier()
; #define PG8_SCHED __builtin_amdgcn_sched_barrier(0)
; template <class Epi, class Sched>
; __device__ __forceinline__ void gemm_phase(LAS unsigned char* lds, const Gemm g, const Sched& S, const Epi& E) {
;     ...
;         for (int t = 0; t < nt; t += 2) {
;             const bool last = (t == nt - 2);
;             const char* a1 = cA + (size_t)(t + 1) * kstep;
;             const char* a2 = last ? nA : cA + (size_t)(t + 2) * kstep; const char* b2 = last ? nB : cB + (size_t)(t + 2) * kstep;
;             const char* a3 = a2 + kstep; const char* b3 = b2 + kstep;
;             PG8_LDB(B0, 0, 0); PG8_LDB(B1, 0, 1); PG8_SCHED; PG8_LDA(At, 0, 0); PG8_STAGE(PG8_SA(1, 1), a1 + hstepA, voffA);
;     ...
;             PG8_LDA(At, 1, 1); PG8_STAGE(PG8_SB(1, 0), b3, voffB); PG8_STAGE(PG8_SB(1, 1), b3 + hstepB, voffB); PG8_STAGE(PG8_SA(1, 0), a3, voffA);
;             PG8_WAIT_V(8); PG8_WAIT_L(0); PG8_BAR; PG8_MMA(1, 0, At, B0); PG8_MMA(1, 1, At, B1); PG8_BAR; PG8_SCHED;
;         }
;         if (wr == 0) PG8_BAR;
	s_add_i32 s0, s0, s20
	v_lshl_add_u64 v[158:159], v[158:159], 0, s[30:31]
	s_mov_b32 m0, s0
	ds_read_b128 v[200:203], v152 offset:49152
	ds_read_b128 v[204:207], v152 offset:50176
	ds_read_b128 v[208:211], v152 offset:51200
	ds_read_b128 v[212:215], v152 offset:52224
	ds_read_b128 v[216:219], v152 offset:53248
	ds_read_b128 v[220:223], v152 offset:54272
	ds_read_b128 v[224:227], v152 offset:55296
	ds_read_b128 v[228:231], v152 offset:56320
	global_load_lds_dwordx4 v[158:159], off
	s_add_i32 m0, s0, 0x2000
	s_add_u32 s6, s6, 0x40080
	v_lshl_add_u64 v[158:159], v[232:233], 0, s[30:31]
	s_addc_u32 s7, s7, 0
	s_add_i32 s0, s26, s20
	global_load_lds_dwordx4 v[158:159], off
	v_lshl_add_u64 v[158:159], s[6:7], 0, v[160:161]
	s_mov_b32 m0, s0
	s_nop 0
	global_load_lds_dwordx4 v[158:159], off
	v_lshl_add_u64 v[158:159], s[6:7], 0, v[136:137]
	s_add_i32 m0, s0, 0x2000
	s_nop 0
	global_load_lds_dwordx4 v[158:159], off
	v_lshl_add_u64 v[158:159], v[234:235], 0, s[30:31]
	s_mov_b32 m0, s24
	s_nop 0
	global_load_lds_dwordx4 v[158:159], off
	v_lshl_add_u64 v[158:159], v[236:237], 0, s[30:31]
	s_mov_b32 m0, s25
	s_nop 0
	global_load_lds_dwordx4 v[158:159], off
	s_waitcnt vmcnt(8)
	s_waitcnt lgkmcnt(0)
	s_barrier
	s_waitcnt lgkmcnt(0)
	v_mfma_f32_16x16x32_bf16 v[64:67], v[142:145], v[200:203], v[64:67]
	v_mfma_f32_16x16x32_bf16 v[60:63], v[162:165], v[200:203], v[60:63]
	v_mfma_f32_16x16x32_bf16 v[48:51], v[142:145], v[208:211], v[48:51]
	v_mfma_f32_16x16x32_bf16 v[44:47], v[162:165], v[208:211], v[44:47]
	v_mfma_f32_16x16x32_bf16 v[32:35], v[142:145], v[216:219], v[32:35]
	v_mfma_f32_16x16x32_bf16 v[28:31], v[162:165], v[216:219], v[28:31]
	v_mfma_f32_16x16x32_bf16 v[16:19], v[142:145], v[224:227], v[16:19]
	v_mfma_f32_16x16x32_bf16 v[12:15], v[162:165], v[224:227], v[12:15]
	v_mfma_f32_16x16x32_bf16 v[64:67], v[154:157], v[204:207], v[64:67]
	v_mfma_f32_16x16x32_bf16 v[60:63], v[166:169], v[204:207], v[60:63]
	v_mfma_f32_16x16x32_bf16 v[48:51], v[154:157], v[212:215], v[48:51]
	v_mfma_f32_16x16x32_bf16 v[44:47], v[166:169], v[212:215], v[44:47]
	v_mfma_f32_16x16x32_bf16 v[32:35], v[154:157], v[220:223], v[32:35]
	v_mfma_f32_16x16x32_bf16 v[28:31], v[166:169], v[220:223], v[28:31]
	v_mfma_f32_16x16x32_bf16 v[16:19], v[154:157], v[228:231], v[16:19]
	v_mfma_f32_16x16x32_bf16 v[12:15], v[166:169], v[228:231], v[12:15]
	v_mfma_f32_16x16x32_bf16 v[56:59], v[170:173], v[200:203], v[56:59]
	v_mfma_f32_16x16x32_bf16 v[52:55], v[190:193], v[200:203], v[52:55]
	v_mfma_f32_16x16x32_bf16 v[40:43], v[170:173], v[208:211], v[40:43]
	v_mfma_f32_16x16x32_bf16 v[36:39], v[190:193], v[208:211], v[36:39]
	v_mfma_f32_16x16x32_bf16 v[24:27], v[170:173], v[216:219], v[24:27]
	v_mfma_f32_16x16x32_bf16 v[20:23], v[190:193], v[216:219], v[20:23]
	v_mfma_f32_16x16x32_bf16 v[8:11], v[170:173], v[224:227], v[8:11]
	v_mfma_f32_16x16x32_bf16 v[4:7], v[190:193], v[224:227], v[4:7]
	v_mfma_f32_16x16x32_bf16 v[56:59], v[174:177], v[204:207], v[56:59]
	v_mfma_f32_16x16x32_bf16 v[52:55], v[196:199], v[204:207], v[52:55]
	v_mfma_f32_16x16x32_bf16 v[40:43], v[174:177], v[212:215], v[40:43]
	v_mfma_f32_16x16x32_bf16 v[36:39], v[196:199], v[212:215], v[36:39]
	v_mfma_f32_16x16x32_bf16 v[24:27], v[174:177], v[220:223], v[24:27]
	v_mfma_f32_16x16x32_bf16 v[20:23], v[196:199], v[220:223], v[20:23]
	v_mfma_f32_16x16x32_bf16 v[8:11], v[174:177], v[228:231], v[8:11]
	v_mfma_f32_16x16x32_bf16 v[4:7], v[196:199], v[228:231], v[4:7]
	s_add_i32 s55, s55, 2
	s_add_u32 s44, s44, 0x100
	s_addc_u32 s45, s45, 0
	s_add_u32 s46, s46, 0x100
	s_addc_u32 s47, s47, 0
	s_add_u32 s0, s44, 0xfffc0080
	s_addc_u32 s6, s45, -1
	s_add_i32 s26, 0, 0x10000
	s_cmp_eq_u32 s55, 12
	s_cselect_b32 s15, s23, s6
	s_cselect_b32 s14, s53, s0
	v_add_u32_e32 v153, s26, v148
	s_cselect_b32 s7, s19, s47
	s_cselect_b32 s6, s54, s46
	s_add_i32 s0, 0, 0x14000
	s_cmp_gt_u32 s55, 13
	s_barrier
	s_cbranch_scc0 .LBB0_718
	s_setprio 0
	s_and_b64 vcc, exec, s[16:17]
	s_cbranch_vccz .LBB0_721
	s_barrier
